# MLA fast loop step A: next segment's store addresses computed behind the last two P.V MFMAs, K base right after the last K read (K.Q^T shadows lighter)
# baseline (speedup 1.0000x reference)
.Lfm_a_exp:
	v_exp_f32_e32 v34, v34
	v_exp_f32_e32 v50, v50
	v_exp_f32_e32 v35, v35
	v_exp_f32_e32 v51, v51
	v_exp_f32_e32 v42, v42
	v_exp_f32_e32 v58, v58
	v_exp_f32_e32 v43, v43
	v_exp_f32_e32 v59, v59
	v_exp_f32_e32 v36, v36
	v_exp_f32_e32 v52, v52
	v_exp_f32_e32 v37, v37
	v_exp_f32_e32 v53, v53
	v_exp_f32_e32 v44, v44
	v_exp_f32_e32 v60, v60
	v_exp_f32_e32 v45, v45
	v_exp_f32_e32 v61, v61
	v_exp_f32_e32 v38, v38
	v_exp_f32_e32 v54, v54
	v_exp_f32_e32 v39, v39
	v_exp_f32_e32 v55, v55
	v_exp_f32_e32 v46, v46
	v_exp_f32_e32 v62, v62
	v_exp_f32_e32 v47, v47
	v_exp_f32_e32 v63, v63
	v_exp_f32_e32 v40, v40
	v_exp_f32_e32 v56, v56
	v_exp_f32_e32 v41, v41
	v_exp_f32_e32 v57, v57
	v_exp_f32_e32 v48, v48
	v_exp_f32_e32 v64, v64
	v_exp_f32_e32 v49, v49
	v_exp_f32_e32 v65, v65
	v_pk_add_f32 v[122:123], v[34:35], v[50:51]
	v_pk_add_f32 v[124:125], v[36:37], v[52:53]
	v_pk_add_f32 v[126:127], v[38:39], v[54:55]
	v_pk_add_f32 v[128:129], v[40:41], v[56:57]
	v_pk_add_f32 v[130:131], v[42:43], v[58:59]
	v_pk_add_f32 v[132:133], v[44:45], v[60:61]
	v_pk_add_f32 v[134:135], v[46:47], v[62:63]
	v_pk_add_f32 v[136:137], v[48:49], v[64:65]
	v_pk_add_f32 v[122:123], v[122:123], v[124:125]
	v_pk_add_f32 v[126:127], v[126:127], v[128:129]
	v_pk_add_f32 v[130:131], v[130:131], v[132:133]
	v_pk_add_f32 v[134:135], v[134:135], v[136:137]
	v_pk_add_f32 v[122:123], v[122:123], v[126:127]
	v_pk_add_f32 v[130:131], v[130:131], v[134:135]
	v_pk_add_f32 v[122:123], v[122:123], v[130:131]
	v_add_f32_e32 v0, v122, v123
	v_cvt_pk_bf16_f32 v122, v34, v35
	v_cvt_pk_bf16_f32 v123, v36, v37
	v_cvt_pk_bf16_f32 v124, v38, v39
	v_cvt_pk_bf16_f32 v125, v40, v41
	v_cvt_pk_bf16_f32 v126, v42, v43
	v_cvt_pk_bf16_f32 v127, v44, v45
	v_cvt_pk_bf16_f32 v128, v46, v47
	v_cvt_pk_bf16_f32 v129, v48, v49
	v_cvt_pk_bf16_f32 v130, v50, v51
	v_cvt_pk_bf16_f32 v131, v52, v53
	v_cvt_pk_bf16_f32 v132, v54, v55
	v_cvt_pk_bf16_f32 v133, v56, v57
	v_cvt_pk_bf16_f32 v134, v58, v59
	v_cvt_pk_bf16_f32 v135, v60, v61
	v_cvt_pk_bf16_f32 v136, v62, v63
	v_cvt_pk_bf16_f32 v137, v64, v65
	v_add_f32_e32 v162, v162, v0
	s_waitcnt lgkmcnt(0)
	s_barrier
	v_mfma_f32_32x32x16_bf16 v[2:17], v[164:167], v[122:125], v[2:17]
	s_setprio 1
	s_waitcnt vmcnt(3)
	ds_write_b128 v190, v[86:89]
	v_mfma_f32_32x32x16_bf16 v[18:33], v[168:171], v[122:125], v[18:33]
	ds_write_b128 v192, v[90:93]
	v_mfma_f32_32x32x16_bf16 v[2:17], v[172:175], v[126:129], v[2:17]
	ds_write_b128 v194, v[82:85] offset:13312
	v_mfma_f32_32x32x16_bf16 v[18:33], v[176:179], v[126:129], v[18:33]
	ds_read_b128 v[236:239], v195
	ds_read_b128 v[240:243], v195 offset:6656
	ds_read_b128 v[244:247], v195 offset:32
	v_mfma_f32_32x32x16_bf16 v[2:17], v[180:183], v[130:133], v[2:17]
	ds_read_b128 v[164:167], v195 offset:6688
	ds_read_b128 v[168:171], v195 offset:64
	ds_read_b128 v[172:175], v195 offset:6720
	v_mfma_f32_32x32x16_bf16 v[18:33], v[220:223], v[130:133], v[18:33]
	ds_read_b128 v[176:179], v195 offset:96
	ds_read_b128 v[180:183], v195 offset:6752
	ds_read_b128 v[220:223], v195 offset:128
	v_mfma_f32_32x32x16_bf16 v[2:17], v[224:227], v[134:137], v[2:17]
	ds_read_b128 v[224:227], v195 offset:6784
	v_add3_u32 v190, s58, v152, v153
	v_add3_u32 v192, s58, v154, v155
	v_mfma_f32_32x32x16_bf16 v[18:33], v[232:235], v[134:137], v[18:33]
	ds_read_b128 v[232:235], v195 offset:160
	v_add3_u32 v194, s58, v156, v140
	s_waitcnt lgkmcnt(9)
	v_mfma_f32_32x32x16_bf16 v[34:49], v[236:239], v[196:199], v[66:81]
	ds_read_b128 v[236:239], v195 offset:6816
	v_mfma_f32_32x32x16_bf16 v[50:65], v[240:243], v[196:199], v[66:81]
	v_add_u32_e32 v195, s57, v157
	s_waitcnt lgkmcnt(7)
	v_mfma_f32_32x32x16_bf16 v[34:49], v[244:247], v[200:203], v[34:49]
	v_add_u32_e32 v248, s60, v160
	s_add_i32 s0, s59, 4
	s_lshl_b32 s8, s0, 6
	v_mfma_f32_32x32x16_bf16 v[50:65], v[164:167], v[200:203], v[50:65]
	ds_read_b128 v[164:167], v248 offset:13312
	s_mul_i32 s0, s8, 0x600
	s_mov_b32 s1, 0
	v_mfma_f32_32x32x16_bf16 v[34:49], v[168:171], v[204:207], v[34:49]
	ds_read_b128 v[168:171], v248 offset:17920
	v_lshl_add_u64 v[82:83], s[0:1], 0, v[186:187]
	v_lshl_add_u64 v[84:85], s[0:1], 0, v[188:189]
	s_waitcnt lgkmcnt(6)
	v_mfma_f32_32x32x16_bf16 v[50:65], v[172:175], v[204:207], v[50:65]
	ds_read_b128 v[172:175], v248 offset:13344
	global_load_dwordx4 v[86:89], v[82:83], off
	global_load_dwordx4 v[90:93], v[84:85], off
	v_mfma_f32_32x32x16_bf16 v[34:49], v[176:179], v[208:211], v[34:49]
	ds_read_b128 v[176:179], v248 offset:17952
	v_lshl_add_u64 v[82:83], s[8:9], 1, v[142:143]
	global_load_dwordx4 v[82:85], v[82:83], off
	v_mfma_f32_32x32x16_bf16 v[50:65], v[180:183], v[208:211], v[50:65]
	ds_read_b128 v[180:183], v248 offset:13376
	s_waitcnt lgkmcnt(6)
	v_mfma_f32_32x32x16_bf16 v[34:49], v[220:223], v[212:215], v[34:49]
	ds_read_b128 v[220:223], v248 offset:17984
	v_mfma_f32_32x32x16_bf16 v[50:65], v[224:227], v[212:215], v[50:65]
	ds_read_b128 v[224:227], v248 offset:13408
	v_mfma_f32_32x32x16_bf16 v[34:49], v[232:235], v[216:219], v[34:49]
	ds_read_b128 v[232:235], v248 offset:18016
	s_waitcnt lgkmcnt(8)
	v_mfma_f32_32x32x16_bf16 v[50:65], v[236:239], v[216:219], v[50:65]
	s_setprio 0
	s_waitcnt lgkmcnt(8)
	s_barrier
	v_max3_f32 v0, v34, v35, v36
	v_max3_f32 v106, v50, v51, v52
	v_max3_f32 v0, v0, v37, v38
	v_max3_f32 v106, v106, v53, v54
	v_max3_f32 v0, v0, v39, v40
	v_max3_f32 v106, v106, v55, v56
	v_max3_f32 v0, v0, v41, v42
	v_max3_f32 v106, v106, v57, v58
	v_max3_f32 v0, v0, v43, v44
	v_max3_f32 v106, v106, v59, v60
	v_max3_f32 v0, v0, v45, v46
	v_max3_f32 v106, v106, v61, v62
	v_max3_f32 v0, v0, v47, v48
	v_max3_f32 v106, v106, v63, v64
	v_max3_f32 v0, v0, v106, v49
	v_max_f32_e32 v0, v0, v65
	v_cmp_lt_f32_e32 vcc, s35, v0
	s_cbranch_vccnz .Lfm_b_resc
